# quarter_row_phase: both 64-lane sums per row as interleaved DPP/permlane butterflies instead of 12 dependent LDS bpermute round trips
# baseline (speedup 1.0000x reference)
; __device__ __forceinline__ float wave_sum(float v) {
; #pragma unroll
;     for (int o = 1; o < 64; o <<= 1) v += shfl_xor_f(v, o);
;     return v;
; }
; __device__ __forceinline__ void quarter_row_phase(const bf16* UTEe, const bf16* UTOo, float* yE, float* yO, int gw, int NGW, int lane) {
;     for (int r = gw; r < 4096; r += NGW) { const v4u* pe = (const v4u*)(UTEe + (size_t)r * 1024) + lane; const v4u* po = (const v4u*)(UTOo + (size_t)r * 1024) + lane; float se = 0.f, so = 0.f;
; #pragma unroll
;         for (int q = 0; q < 2; ++q) { const v4u ve = pe[64 * q], vo = po[64 * q];
; #pragma unroll
;             for (int e = 0; e < 4; ++e) { se += bflo(ve[e]) - bfhi(ve[e]); so += bflo(vo[e]) - bfhi(vo[e]); } }
;         se = wave_sum(se); so = wave_sum(so); if (lane == 0) { yE[r] = se * (1.f / 64.f); yO[r] = so * (1.f / 64.f); } }
.LBB0_635:
	v_lshl_add_u64 v[6:7], v[0:1], 0, s[60:61]
	v_add_co_u32_e32 v10, vcc, 0x2f800000, v6
	s_nop 1
	v_addc_co_u32_e32 v11, vcc, 0, v7, vcc
	v_add_co_u32_e32 v12, vcc, 0x31000000, v6
	s_waitcnt lgkmcnt(0)
	global_load_dwordx4 v[2:5], v[10:11], off
	v_addc_co_u32_e32 v13, vcc, 0, v7, vcc
	global_load_dwordx4 v[6:9], v[12:13], off
	s_waitcnt vmcnt(0)
	v_lshlrev_b32_e32 v14, 16, v2
	v_and_b32_e32 v2, 0xffff0000, v2
	v_sub_f32_e32 v2, v14, v2
	v_lshlrev_b32_e32 v14, 16, v6
	v_and_b32_e32 v6, 0xffff0000, v6
	v_sub_f32_e32 v6, v14, v6
	v_lshlrev_b32_e32 v14, 16, v3
	v_and_b32_e32 v3, 0xffff0000, v3
	v_add_f32_e32 v2, 0, v2
	v_sub_f32_e32 v3, v14, v3
	v_add_f32_e32 v2, v3, v2
	v_lshlrev_b32_e32 v3, 16, v7
	v_and_b32_e32 v7, 0xffff0000, v7
	v_add_f32_e32 v6, 0, v6
	v_sub_f32_e32 v3, v3, v7
	v_add_f32_e32 v3, v3, v6
	v_lshlrev_b32_e32 v6, 16, v4
	v_and_b32_e32 v4, 0xffff0000, v4
	v_sub_f32_e32 v4, v6, v4
	v_add_f32_e32 v2, v4, v2
	v_lshlrev_b32_e32 v4, 16, v8
	v_and_b32_e32 v6, 0xffff0000, v8
	v_sub_f32_e32 v4, v4, v6
	v_add_f32_e32 v3, v4, v3
	v_lshlrev_b32_e32 v4, 16, v5
	v_and_b32_e32 v5, 0xffff0000, v5
	v_sub_f32_e32 v4, v4, v5
	v_add_f32_e32 v14, v4, v2
	v_lshlrev_b32_e32 v2, 16, v9
	v_and_b32_e32 v4, 0xffff0000, v9
	v_sub_f32_e32 v2, v2, v4
	v_add_f32_e32 v15, v2, v3
	global_load_dwordx4 v[2:5], v[10:11], off offset:1024
	global_load_dwordx4 v[6:9], v[12:13], off offset:1024
	s_waitcnt vmcnt(1)
	v_lshlrev_b32_e32 v10, 16, v2
	v_and_b32_e32 v2, 0xffff0000, v2
	v_sub_f32_e32 v2, v10, v2
	s_waitcnt vmcnt(0)
	v_lshlrev_b32_e32 v10, 16, v6
	v_and_b32_e32 v6, 0xffff0000, v6
	v_sub_f32_e32 v6, v10, v6
	v_lshlrev_b32_e32 v10, 16, v3
	v_and_b32_e32 v3, 0xffff0000, v3
	v_add_f32_e32 v2, v2, v14
	v_sub_f32_e32 v3, v10, v3
	v_add_f32_e32 v2, v3, v2
	v_lshlrev_b32_e32 v3, 16, v7
	v_and_b32_e32 v7, 0xffff0000, v7
	v_add_f32_e32 v6, v6, v15
	v_sub_f32_e32 v3, v3, v7
	v_add_f32_e32 v3, v3, v6
	v_lshlrev_b32_e32 v6, 16, v4
	v_and_b32_e32 v4, 0xffff0000, v4
	v_sub_f32_e32 v4, v6, v4
	v_add_f32_e32 v2, v4, v2
	v_lshlrev_b32_e32 v4, 16, v8
	v_and_b32_e32 v6, 0xffff0000, v8
	v_sub_f32_e32 v4, v4, v6
	v_add_f32_e32 v3, v4, v3
	v_lshlrev_b32_e32 v4, 16, v5
	v_and_b32_e32 v5, 0xffff0000, v5
	v_sub_f32_e32 v4, v4, v5
	v_add_f32_e32 v2, v4, v2
	v_lshlrev_b32_e32 v4, 16, v9
	v_and_b32_e32 v5, 0xffff0000, v9
	v_sub_f32_e32 v4, v4, v5
	v_add_f32_e32 v4, v4, v3
	s_nop 1
	v_add_f32_dpp v2, v2, v2 quad_perm:[1,0,3,2] row_mask:0xf bank_mask:0xf
	v_add_f32_dpp v4, v4, v4 quad_perm:[1,0,3,2] row_mask:0xf bank_mask:0xf
	s_nop 0
	v_add_f32_dpp v2, v2, v2 quad_perm:[2,3,0,1] row_mask:0xf bank_mask:0xf
	v_add_f32_dpp v4, v4, v4 quad_perm:[2,3,0,1] row_mask:0xf bank_mask:0xf
	s_nop 0
	v_add_f32_dpp v2, v2, v2 row_half_mirror row_mask:0xf bank_mask:0xf
	v_add_f32_dpp v4, v4, v4 row_half_mirror row_mask:0xf bank_mask:0xf
	s_nop 0
	v_add_f32_dpp v2, v2, v2 row_mirror row_mask:0xf bank_mask:0xf
	v_add_f32_dpp v4, v4, v4 row_mirror row_mask:0xf bank_mask:0xf
	s_nop 0
	v_mov_b32_e32 v3, v2
	v_mov_b32_e32 v5, v4
	s_nop 1
	v_permlane16_swap_b32_e32 v3, v2
	v_permlane16_swap_b32_e32 v5, v4
	s_nop 1
	v_add_f32_e32 v2, v2, v3
	v_add_f32_e32 v4, v4, v5
	v_mov_b32_e32 v3, v2
	v_mov_b32_e32 v5, v4
	s_nop 1
	v_permlane32_swap_b32_e32 v3, v2
	v_permlane32_swap_b32_e32 v5, v4
	s_nop 1
	s_and_saveexec_b64 s[72:73], s[4:5]
	s_cbranch_execz .LBB0_634
	s_add_u32 s14, s8, s60
	v_add_f32_e32 v2, v2, v3
	s_addc_u32 s15, s9, 0
	s_waitcnt lgkmcnt(0)
	v_add_f32_e32 v4, v4, v5
	v_mul_f32_e32 v2, 0x3c800000, v2
	v_mov_b32_e32 v3, 0x7c0000
	v_mul_f32_e32 v4, 0x3c800000, v4
	global_store_dword v3, v2, s[14:15]
	v_mov_b32_e32 v2, 0x7c4000
	global_store_dword v2, v4, s[14:15]
	s_branch .LBB0_634
